# GEMM k-loops (gres1, gres2, kvq): LDS stores interleaved two-at-a-time behind each fragment-read group with counted lgkmcnt, vmcnt wait at the head of the half
# speedup vs baseline: 1.0180x; 1.0146x over previous
.LBB0_886:
	s_mov_b64 vcc, s[6:7]
	s_cbranch_vccnz .Lg1w_w0
	s_waitcnt vmcnt(8)
	s_branch .Lg1w_w1

.Lg1w_w1:
	v_add_u32_e32 v151, v142, v143
	ds_read_b128 v[154:157], v151
	v_add_u32_e32 v152, v142, v145
	ds_read_b128 v[158:161], v152 offset:16384
	ds_read_b128 v[162:165], v151 offset:4096
	ds_read_b128 v[166:169], v152 offset:20480
	ds_write_b128 v141, v[68:71] offset:32768
	ds_write_b128 v141, v[76:79] offset:49152
	v_add_u32_e32 v153, v148, v143
	s_waitcnt lgkmcnt(2)
	v_mfma_f32_32x32x16_bf16 v[16:31], v[162:165], v[158:161], v[16:31]
	s_cmp_gt_u32 s39, 12
	v_mfma_f32_32x32x16_bf16 v[48:63], v[154:157], v[158:161], v[48:63]
	v_mfma_f32_32x32x16_bf16 v[32:47], v[154:157], v[166:169], v[32:47]
	ds_read_b128 v[156:159], v153
	v_add_u32_e32 v154, v148, v145
	v_add_u32_e32 v155, v149, v143
	v_mfma_f32_32x32x16_bf16 v[0:15], v[162:165], v[166:169], v[0:15]
	ds_read_b128 v[160:163], v154 offset:16384
	ds_read_b128 v[164:167], v153 offset:4096
	ds_read_b128 v[168:171], v154 offset:20480
	ds_write_b128 v141, v[84:87] offset:36864
	ds_write_b128 v141, v[92:95] offset:53248
	s_waitcnt lgkmcnt(2)
	v_mfma_f32_32x32x16_bf16 v[48:63], v[156:159], v[160:163], v[48:63]
	v_mfma_f32_32x32x16_bf16 v[32:47], v[156:159], v[168:171], v[32:47]
	v_add_u32_e32 v156, v149, v145
	v_add_u32_e32 v157, v150, v143
	v_mfma_f32_32x32x16_bf16 v[16:31], v[164:167], v[160:163], v[16:31]
	ds_read_b128 v[158:161], v155
	v_mfma_f32_32x32x16_bf16 v[0:15], v[164:167], v[168:171], v[0:15]
	ds_read_b128 v[162:165], v156 offset:16384
	ds_read_b128 v[166:169], v155 offset:4096
	ds_read_b128 v[170:173], v156 offset:20480
	ds_write_b128 v141, v[100:103] offset:40960
	ds_write_b128 v141, v[108:111] offset:57344
	s_waitcnt lgkmcnt(2)
	v_mfma_f32_32x32x16_bf16 v[48:63], v[158:161], v[162:165], v[48:63]
	v_mfma_f32_32x32x16_bf16 v[32:47], v[158:161], v[170:173], v[32:47]
	v_add_u32_e32 v158, v150, v145
	v_mfma_f32_32x32x16_bf16 v[16:31], v[166:169], v[162:165], v[16:31]
	ds_read_b128 v[160:163], v157
	v_mfma_f32_32x32x16_bf16 v[0:15], v[166:169], v[170:173], v[0:15]
	ds_read_b128 v[164:167], v158 offset:16384
	ds_read_b128 v[168:171], v157 offset:4096
	ds_read_b128 v[172:175], v158 offset:20480
	ds_write_b128 v141, v[116:119] offset:45056
	ds_write_b128 v141, v[124:127] offset:61440
	s_waitcnt lgkmcnt(2)
	v_mfma_f32_32x32x16_bf16 v[48:63], v[160:163], v[164:167], v[48:63]
	v_mfma_f32_32x32x16_bf16 v[32:47], v[160:163], v[172:175], v[32:47]
	v_mfma_f32_32x32x16_bf16 v[16:31], v[168:171], v[164:167], v[16:31]
	v_mfma_f32_32x32x16_bf16 v[0:15], v[168:171], v[172:175], v[0:15]
	s_waitcnt lgkmcnt(0)
	s_barrier
	s_cbranch_scc1 .LBB0_888
	v_add_co_u32_e32 v84, vcc, 0x10000, v136
	global_load_dwordx4 v[68:71], v[136:137], off offset:384
	global_load_dwordx4 v[76:79], v[134:135], off offset:384
	v_addc_co_u32_e32 v85, vcc, 0, v137, vcc
	v_add_co_u32_e32 v92, vcc, 0x10000, v134
	global_load_dwordx4 v[84:87], v[84:85], off offset:384
	s_nop 0
	v_addc_co_u32_e32 v93, vcc, 0, v135, vcc
	v_add_co_u32_e32 v100, vcc, 0x20000, v136
	global_load_dwordx4 v[92:95], v[92:93], off offset:384
	s_nop 0
	v_addc_co_u32_e32 v101, vcc, 0, v137, vcc
	v_add_co_u32_e32 v108, vcc, 0x20000, v134
	global_load_dwordx4 v[100:103], v[100:101], off offset:384
	s_nop 0
	v_addc_co_u32_e32 v109, vcc, 0, v135, vcc
	v_add_co_u32_e32 v116, vcc, 0x30000, v136
	global_load_dwordx4 v[108:111], v[108:109], off offset:384
	s_nop 0
	v_addc_co_u32_e32 v117, vcc, 0, v137, vcc
	v_add_co_u32_e32 v124, vcc, 0x30000, v134
	global_load_dwordx4 v[116:119], v[116:117], off offset:384
	s_nop 0
	v_addc_co_u32_e32 v125, vcc, 0, v135, vcc
	global_load_dwordx4 v[124:127], v[124:125], off offset:384
.LBB0_888:
	s_waitcnt vmcnt(8)
	ds_read_b128 v[134:137], v151 offset:32768
	ds_read_b128 v[160:163], v152 offset:49152
	ds_read_b128 v[164:167], v151 offset:36864
	ds_read_b128 v[168:171], v152 offset:53248
	ds_write_b128 v141, v[64:67]
	ds_write_b128 v141, v[72:75] offset:16384
	s_andn2_b64 vcc, exec, s[8:9]
	s_waitcnt lgkmcnt(2)
	v_mfma_f32_32x32x16_bf16 v[48:63], v[134:137], v[160:163], v[48:63]
	v_mfma_f32_32x32x16_bf16 v[32:47], v[134:137], v[168:171], v[32:47]
	v_mfma_f32_32x32x16_bf16 v[16:31], v[164:167], v[160:163], v[16:31]
	v_mfma_f32_32x32x16_bf16 v[0:15], v[164:167], v[168:171], v[0:15]
	ds_read_b128 v[134:137], v153 offset:32768
	ds_read_b128 v[160:163], v154 offset:49152
	ds_read_b128 v[164:167], v153 offset:36864
	ds_read_b128 v[168:171], v154 offset:53248
	ds_write_b128 v141, v[80:83] offset:4096
	ds_write_b128 v141, v[88:91] offset:20480
	s_waitcnt lgkmcnt(2)
	v_mfma_f32_32x32x16_bf16 v[48:63], v[134:137], v[160:163], v[48:63]
	v_mfma_f32_32x32x16_bf16 v[32:47], v[134:137], v[168:171], v[32:47]
	v_mfma_f32_32x32x16_bf16 v[16:31], v[164:167], v[160:163], v[16:31]
	v_mfma_f32_32x32x16_bf16 v[0:15], v[164:167], v[168:171], v[0:15]
	ds_read_b128 v[134:137], v155 offset:32768
	ds_read_b128 v[160:163], v156 offset:49152
	ds_read_b128 v[152:155], v155 offset:36864
	ds_read_b128 v[164:167], v156 offset:53248
	ds_write_b128 v141, v[96:99] offset:8192
	ds_write_b128 v141, v[104:107] offset:24576
	s_waitcnt lgkmcnt(2)
	v_mfma_f32_32x32x16_bf16 v[48:63], v[134:137], v[160:163], v[48:63]
	v_mfma_f32_32x32x16_bf16 v[32:47], v[134:137], v[164:167], v[32:47]
	v_mfma_f32_32x32x16_bf16 v[16:31], v[152:155], v[160:163], v[16:31]
	v_mfma_f32_32x32x16_bf16 v[0:15], v[152:155], v[164:167], v[0:15]
	ds_read_b128 v[134:137], v157 offset:32768
	ds_read_b128 v[152:155], v158 offset:49152
	ds_read_b128 v[160:163], v157 offset:36864
	ds_read_b128 v[156:159], v158 offset:53248
	ds_write_b128 v141, v[112:115] offset:12288
	ds_write_b128 v141, v[120:123] offset:28672
	s_waitcnt lgkmcnt(2)
	v_mfma_f32_32x32x16_bf16 v[48:63], v[134:137], v[152:155], v[48:63]
	v_mfma_f32_32x32x16_bf16 v[32:47], v[134:137], v[156:159], v[32:47]
	v_mfma_f32_32x32x16_bf16 v[16:31], v[160:163], v[152:155], v[16:31]
	v_mfma_f32_32x32x16_bf16 v[0:15], v[160:163], v[156:159], v[0:15]
	s_branch .LBB0_883

.LBB0_1010:
	s_mov_b64 vcc, s[0:1]
	s_cbranch_vccnz .Lkqw_w0
	s_waitcnt vmcnt(8)
	s_branch .Lkqw_w1

.Lkqw_w1:
	v_add_u32_e32 v153, v137, v139
	ds_read_b128 v[218:221], v153
	v_add_u32_e32 v155, v137, v141
	ds_read_b128 v[222:225], v155 offset:16384
	ds_read_b128 v[226:229], v153 offset:4096
	ds_read_b128 v[230:233], v155 offset:20480
	ds_write_b128 v135, v[68:71] offset:32768
	ds_write_b128 v135, v[76:79] offset:49152
	v_add_u32_e32 v157, v143, v139
	s_waitcnt lgkmcnt(2)
	v_mfma_f32_32x32x16_bf16 v[0:15], v[226:229], v[222:225], v[0:15]
	v_add_u32_e32 v159, v143, v141
	v_add_u32_e32 v161, v149, v139
	v_add_u32_e32 v163, v149, v141
	v_add_u32_e32 v165, v151, v139
	v_add_u32_e32 v167, v151, v141
	s_cmp_gt_u32 s68, 12
	v_mfma_f32_32x32x16_bf16 v[32:47], v[218:221], v[222:225], v[32:47]
	v_mfma_f32_32x32x16_bf16 v[48:63], v[218:221], v[230:233], v[48:63]
	ds_read_b128 v[218:221], v157
	v_mfma_f32_32x32x16_bf16 v[16:31], v[226:229], v[230:233], v[16:31]
	ds_read_b128 v[222:225], v159 offset:16384
	ds_read_b128 v[226:229], v157 offset:4096
	ds_read_b128 v[230:233], v159 offset:20480
	ds_write_b128 v135, v[84:87] offset:36864
	ds_write_b128 v135, v[92:95] offset:53248
	s_waitcnt lgkmcnt(2)
	v_mfma_f32_32x32x16_bf16 v[32:47], v[218:221], v[222:225], v[32:47]
	v_mfma_f32_32x32x16_bf16 v[48:63], v[218:221], v[230:233], v[48:63]
	ds_read_b128 v[218:221], v161
	v_mfma_f32_32x32x16_bf16 v[0:15], v[226:229], v[222:225], v[0:15]
	v_mfma_f32_32x32x16_bf16 v[16:31], v[226:229], v[230:233], v[16:31]
	ds_read_b128 v[222:225], v163 offset:16384
	ds_read_b128 v[226:229], v161 offset:4096
	ds_read_b128 v[230:233], v163 offset:20480
	ds_write_b128 v135, v[100:103] offset:40960
	ds_write_b128 v135, v[108:111] offset:57344
	s_waitcnt lgkmcnt(2)
	v_mfma_f32_32x32x16_bf16 v[32:47], v[218:221], v[222:225], v[32:47]
	v_mfma_f32_32x32x16_bf16 v[48:63], v[218:221], v[230:233], v[48:63]
	ds_read_b128 v[218:221], v165
	v_mfma_f32_32x32x16_bf16 v[0:15], v[226:229], v[222:225], v[0:15]
	v_mfma_f32_32x32x16_bf16 v[16:31], v[226:229], v[230:233], v[16:31]
	ds_read_b128 v[222:225], v167 offset:16384
	ds_read_b128 v[226:229], v165 offset:4096
	ds_read_b128 v[230:233], v167 offset:20480
	ds_write_b128 v135, v[116:119] offset:45056
	ds_write_b128 v135, v[124:127] offset:61440
	s_waitcnt lgkmcnt(2)
	v_mfma_f32_32x32x16_bf16 v[32:47], v[218:221], v[222:225], v[32:47]
	v_mfma_f32_32x32x16_bf16 v[48:63], v[218:221], v[230:233], v[48:63]
	v_mfma_f32_32x32x16_bf16 v[0:15], v[226:229], v[222:225], v[0:15]
	v_mfma_f32_32x32x16_bf16 v[16:31], v[226:229], v[230:233], v[16:31]
	s_waitcnt lgkmcnt(0)
	s_barrier
	s_cbranch_scc1 .LBB0_1012
	v_add_co_u32_e32 v84, vcc, 0x10000, v194
	global_load_dwordx4 v[68:71], v[194:195], off offset:384
	global_load_dwordx4 v[76:79], v[192:193], off offset:384
	v_addc_co_u32_e32 v85, vcc, 0, v195, vcc
	v_add_co_u32_e32 v92, vcc, 0x10000, v192
	global_load_dwordx4 v[84:87], v[84:85], off offset:384
	s_nop 0
	v_addc_co_u32_e32 v93, vcc, 0, v193, vcc
	v_add_co_u32_e32 v100, vcc, 0x20000, v194
	global_load_dwordx4 v[92:95], v[92:93], off offset:384
	s_nop 0
	v_addc_co_u32_e32 v101, vcc, 0, v195, vcc
	v_add_co_u32_e32 v108, vcc, 0x20000, v192
	global_load_dwordx4 v[100:103], v[100:101], off offset:384
	s_nop 0
	v_addc_co_u32_e32 v109, vcc, 0, v193, vcc
	v_add_co_u32_e32 v116, vcc, 0x30000, v194
	global_load_dwordx4 v[108:111], v[108:109], off offset:384
	s_nop 0
	v_addc_co_u32_e32 v117, vcc, 0, v195, vcc
	v_add_co_u32_e32 v124, vcc, 0x30000, v192
	global_load_dwordx4 v[116:119], v[116:117], off offset:384
	s_nop 0
	v_addc_co_u32_e32 v125, vcc, 0, v193, vcc
	global_load_dwordx4 v[124:127], v[124:125], off offset:384
.LBB0_1012:
	s_waitcnt vmcnt(8)
	ds_read_b128 v[192:195], v153 offset:32768
	ds_read_b128 v[218:221], v155 offset:49152
	ds_read_b128 v[222:225], v153 offset:36864
	ds_read_b128 v[226:229], v155 offset:53248
	ds_write_b128 v135, v[64:67]
	ds_write_b128 v135, v[72:75] offset:16384
	s_andn2_b64 vcc, exec, s[8:9]
	s_waitcnt lgkmcnt(2)
	v_mfma_f32_32x32x16_bf16 v[32:47], v[192:195], v[218:221], v[32:47]
	v_mfma_f32_32x32x16_bf16 v[48:63], v[192:195], v[226:229], v[48:63]
	v_mfma_f32_32x32x16_bf16 v[0:15], v[222:225], v[218:221], v[0:15]
	v_mfma_f32_32x32x16_bf16 v[16:31], v[222:225], v[226:229], v[16:31]
	ds_read_b128 v[192:195], v157 offset:32768
	ds_read_b128 v[218:221], v159 offset:49152
	ds_read_b128 v[222:225], v157 offset:36864
	ds_read_b128 v[226:229], v159 offset:53248
	ds_write_b128 v135, v[80:83] offset:4096
	ds_write_b128 v135, v[88:91] offset:20480
	s_waitcnt lgkmcnt(2)
	v_mfma_f32_32x32x16_bf16 v[32:47], v[192:195], v[218:221], v[32:47]
	v_mfma_f32_32x32x16_bf16 v[48:63], v[192:195], v[226:229], v[48:63]
	v_mfma_f32_32x32x16_bf16 v[0:15], v[222:225], v[218:221], v[0:15]
	v_mfma_f32_32x32x16_bf16 v[16:31], v[222:225], v[226:229], v[16:31]
	ds_read_b128 v[192:195], v161 offset:32768
	ds_read_b128 v[218:221], v163 offset:49152
	ds_read_b128 v[222:225], v161 offset:36864
	ds_read_b128 v[226:229], v163 offset:53248
	ds_write_b128 v135, v[96:99] offset:8192
	ds_write_b128 v135, v[104:107] offset:24576
	s_waitcnt lgkmcnt(2)
	v_mfma_f32_32x32x16_bf16 v[32:47], v[192:195], v[218:221], v[32:47]
	v_mfma_f32_32x32x16_bf16 v[48:63], v[192:195], v[226:229], v[48:63]
	v_mfma_f32_32x32x16_bf16 v[0:15], v[222:225], v[218:221], v[0:15]
	v_mfma_f32_32x32x16_bf16 v[16:31], v[222:225], v[226:229], v[16:31]
	ds_read_b128 v[192:195], v165 offset:32768
	ds_read_b128 v[218:221], v167 offset:49152
	ds_read_b128 v[222:225], v165 offset:36864
	ds_read_b128 v[226:229], v167 offset:53248
	ds_write_b128 v135, v[112:115] offset:12288
	ds_write_b128 v135, v[120:123] offset:28672
	s_waitcnt lgkmcnt(2)
	v_mfma_f32_32x32x16_bf16 v[32:47], v[192:195], v[218:221], v[32:47]
	v_mfma_f32_32x32x16_bf16 v[48:63], v[192:195], v[226:229], v[48:63]
	v_mfma_f32_32x32x16_bf16 v[0:15], v[222:225], v[218:221], v[0:15]
	v_mfma_f32_32x32x16_bf16 v[16:31], v[222:225], v[226:229], v[16:31]
	s_branch .LBB0_1007

.LBB0_1508:
	s_mov_b64 vcc, s[4:5]
	s_cbranch_vccnz .Lg2w_w0
	s_waitcnt vmcnt(8)
	s_branch .Lg2w_w1

.Lg2w_w1:
	v_add_u32_e32 v145, v139, v140
	ds_read_b128 v[148:151], v145
	v_add_u32_e32 v146, v139, v141
	ds_read_b128 v[152:155], v146 offset:16384
	ds_read_b128 v[156:159], v145 offset:4096
	ds_read_b128 v[160:163], v146 offset:20480
	ds_write_b128 v138, v[68:71] offset:32768
	ds_write_b128 v138, v[76:79] offset:49152
	v_add_u32_e32 v147, v142, v140
	s_waitcnt lgkmcnt(2)
	v_mfma_f32_32x32x16_bf16 v[16:31], v[156:159], v[152:155], v[16:31]
	s_cmp_gt_u32 s16, 12
	v_mfma_f32_32x32x16_bf16 v[48:63], v[148:151], v[152:155], v[48:63]
	v_mfma_f32_32x32x16_bf16 v[32:47], v[148:151], v[160:163], v[32:47]
	ds_read_b128 v[150:153], v147
	v_add_u32_e32 v148, v142, v141
	v_add_u32_e32 v149, v143, v140
	v_mfma_f32_32x32x16_bf16 v[0:15], v[156:159], v[160:163], v[0:15]
	ds_read_b128 v[154:157], v148 offset:16384
	ds_read_b128 v[158:161], v147 offset:4096
	ds_read_b128 v[162:165], v148 offset:20480
	ds_write_b128 v138, v[84:87] offset:36864
	ds_write_b128 v138, v[92:95] offset:53248
	s_waitcnt lgkmcnt(2)
	v_mfma_f32_32x32x16_bf16 v[48:63], v[150:153], v[154:157], v[48:63]
	v_mfma_f32_32x32x16_bf16 v[32:47], v[150:153], v[162:165], v[32:47]
	v_add_u32_e32 v150, v143, v141
	v_add_u32_e32 v151, v144, v140
	v_mfma_f32_32x32x16_bf16 v[16:31], v[158:161], v[154:157], v[16:31]
	ds_read_b128 v[152:155], v149
	v_mfma_f32_32x32x16_bf16 v[0:15], v[158:161], v[162:165], v[0:15]
	ds_read_b128 v[156:159], v150 offset:16384
	ds_read_b128 v[160:163], v149 offset:4096
	ds_read_b128 v[170:173], v150 offset:20480
	ds_write_b128 v138, v[100:103] offset:40960
	ds_write_b128 v138, v[108:111] offset:57344
	s_waitcnt lgkmcnt(2)
	v_mfma_f32_32x32x16_bf16 v[48:63], v[152:155], v[156:159], v[48:63]
	v_mfma_f32_32x32x16_bf16 v[32:47], v[152:155], v[170:173], v[32:47]
	v_add_u32_e32 v152, v144, v141
	v_mfma_f32_32x32x16_bf16 v[16:31], v[160:163], v[156:159], v[16:31]
	ds_read_b128 v[154:157], v151
	v_mfma_f32_32x32x16_bf16 v[0:15], v[160:163], v[170:173], v[0:15]
	ds_read_b128 v[158:161], v152 offset:16384
	ds_read_b128 v[162:165], v151 offset:4096
	ds_read_b128 v[170:173], v152 offset:20480
	ds_write_b128 v138, v[116:119] offset:45056
	ds_write_b128 v138, v[124:127] offset:61440
	s_waitcnt lgkmcnt(2)
	v_mfma_f32_32x32x16_bf16 v[48:63], v[154:157], v[158:161], v[48:63]
	v_mfma_f32_32x32x16_bf16 v[32:47], v[154:157], v[170:173], v[32:47]
	v_mfma_f32_32x32x16_bf16 v[16:31], v[162:165], v[158:161], v[16:31]
	v_mfma_f32_32x32x16_bf16 v[0:15], v[162:165], v[170:173], v[0:15]
	s_waitcnt lgkmcnt(0)
	s_barrier
	s_cbranch_scc1 .LBB0_1510
	v_add_co_u32_e32 v84, vcc, 0x10000, v136
	global_load_dwordx4 v[68:71], v[136:137], off offset:384
	global_load_dwordx4 v[76:79], v[134:135], off offset:384
	v_addc_co_u32_e32 v85, vcc, 0, v137, vcc
	v_add_co_u32_e32 v92, vcc, 0x10000, v134
	global_load_dwordx4 v[84:87], v[84:85], off offset:384
	s_nop 0
	v_addc_co_u32_e32 v93, vcc, 0, v135, vcc
	v_add_co_u32_e32 v100, vcc, 0x20000, v136
	global_load_dwordx4 v[92:95], v[92:93], off offset:384
	s_nop 0
	v_addc_co_u32_e32 v101, vcc, 0, v137, vcc
	v_add_co_u32_e32 v108, vcc, 0x20000, v134
	global_load_dwordx4 v[100:103], v[100:101], off offset:384
	s_nop 0
	v_addc_co_u32_e32 v109, vcc, 0, v135, vcc
	v_add_co_u32_e32 v116, vcc, 0x30000, v136
	global_load_dwordx4 v[108:111], v[108:109], off offset:384
	s_nop 0
	v_addc_co_u32_e32 v117, vcc, 0, v137, vcc
	v_add_co_u32_e32 v124, vcc, 0x30000, v134
	global_load_dwordx4 v[116:119], v[116:117], off offset:384
	s_nop 0
	v_addc_co_u32_e32 v125, vcc, 0, v135, vcc
	global_load_dwordx4 v[124:127], v[124:125], off offset:384
.LBB0_1510:
	s_waitcnt vmcnt(8)
	ds_read_b128 v[134:137], v145 offset:32768
	ds_read_b128 v[154:157], v146 offset:49152
	ds_read_b128 v[158:161], v145 offset:36864
	ds_read_b128 v[162:165], v146 offset:53248
	ds_write_b128 v138, v[64:67]
	ds_write_b128 v138, v[72:75] offset:16384
	s_andn2_b64 vcc, exec, s[6:7]
	s_waitcnt lgkmcnt(2)
	v_mfma_f32_32x32x16_bf16 v[48:63], v[134:137], v[154:157], v[48:63]
	v_mfma_f32_32x32x16_bf16 v[32:47], v[134:137], v[162:165], v[32:47]
	v_mfma_f32_32x32x16_bf16 v[16:31], v[158:161], v[154:157], v[16:31]
	v_mfma_f32_32x32x16_bf16 v[0:15], v[158:161], v[162:165], v[0:15]
	ds_read_b128 v[134:137], v147 offset:32768
	ds_read_b128 v[154:157], v148 offset:49152
	ds_read_b128 v[158:161], v147 offset:36864
	ds_read_b128 v[162:165], v148 offset:53248
	ds_write_b128 v138, v[80:83] offset:4096
	ds_write_b128 v138, v[88:91] offset:20480
	s_waitcnt lgkmcnt(2)
	v_mfma_f32_32x32x16_bf16 v[48:63], v[134:137], v[154:157], v[48:63]
	v_mfma_f32_32x32x16_bf16 v[32:47], v[134:137], v[162:165], v[32:47]
	v_mfma_f32_32x32x16_bf16 v[16:31], v[158:161], v[154:157], v[16:31]
	v_mfma_f32_32x32x16_bf16 v[0:15], v[158:161], v[162:165], v[0:15]
	ds_read_b128 v[134:137], v149 offset:32768
	ds_read_b128 v[154:157], v150 offset:49152
	ds_read_b128 v[146:149], v149 offset:36864
	ds_read_b128 v[158:161], v150 offset:53248
	ds_write_b128 v138, v[96:99] offset:8192
	ds_write_b128 v138, v[104:107] offset:24576
	s_waitcnt lgkmcnt(2)
	v_mfma_f32_32x32x16_bf16 v[48:63], v[134:137], v[154:157], v[48:63]
	v_mfma_f32_32x32x16_bf16 v[32:47], v[134:137], v[158:161], v[32:47]
	v_mfma_f32_32x32x16_bf16 v[16:31], v[146:149], v[154:157], v[16:31]
	v_mfma_f32_32x32x16_bf16 v[0:15], v[146:149], v[158:161], v[0:15]
	ds_read_b128 v[134:137], v151 offset:32768
	ds_read_b128 v[146:149], v152 offset:49152
	ds_read_b128 v[154:157], v151 offset:36864
	ds_read_b128 v[150:153], v152 offset:53248
	ds_write_b128 v138, v[112:115] offset:12288
	ds_write_b128 v138, v[120:123] offset:28672
	s_waitcnt lgkmcnt(2)
	v_mfma_f32_32x32x16_bf16 v[48:63], v[134:137], v[146:149], v[48:63]
	v_mfma_f32_32x32x16_bf16 v[32:47], v[134:137], v[150:153], v[32:47]
	v_mfma_f32_32x32x16_bf16 v[16:31], v[154:157], v[146:149], v[16:31]
	v_mfma_f32_32x32x16_bf16 v[0:15], v[154:157], v[150:153], v[0:15]
	s_branch .LBB0_1505
